# attention: drop mid-loop vmcnt(0), pipelined K-fragment LDS reads in QK (MoBA+dilated), branch-free dilated window mask
# speedup vs baseline: 1.0109x; 1.0109x over previous
.LBB0_298:
	s_and_b64 vcc, exec, s[52:53]
	s_cbranch_vccnz .LBB0_290
	s_and_b32 s52, s58, 0x4000
	v_add_u32_e32 v0, s52, v178
	v_add_u32_e32 v14, v0, v181
	ds_read_b128 v[2:5], v14
	ds_read_b128 v[6:9], v14 offset:8192
	v_add_u32_e32 v15, v0, v182
	ds_read_b128 v[10:13], v15
	ds_read_b128 v[246:249], v15 offset:8192
	v_mov_b32_e32 v81, v80
	v_mov_b32_e32 v82, v80
	v_mov_b32_e32 v83, v80
	v_mov_b32_e32 v84, v80
	v_mov_b32_e32 v85, v80
	v_mov_b32_e32 v86, v80
	v_mov_b32_e32 v87, v80
	v_mov_b32_e32 v88, v80
	v_mov_b32_e32 v89, v80
	v_mov_b32_e32 v90, v80
	v_mov_b32_e32 v91, v80
	v_mov_b32_e32 v92, v80
	v_mov_b32_e32 v93, v80
	v_mov_b32_e32 v94, v80
	v_mov_b32_e32 v95, v80
	s_andn2_b64 vcc, exec, s[2:3]
	s_waitcnt lgkmcnt(3)
	v_mfma_f32_32x32x16_bf16 v[96:111], v[2:5], v[112:115], v[80:95]
	v_add_u32_e32 v14, v0, v183
	ds_read_b128 v[250:253], v14
	s_waitcnt lgkmcnt(3)
	v_mfma_f32_32x32x16_bf16 v[80:95], v[6:9], v[112:115], v[80:95]
	ds_read_b128 v[2:5], v14 offset:8192
	s_waitcnt lgkmcnt(3)
	v_mfma_f32_32x32x16_bf16 v[96:111], v[10:13], v[116:119], v[96:111]
	v_add_u32_e32 v15, v0, v184
	ds_read_b128 v[6:9], v15
	s_waitcnt lgkmcnt(3)
	v_mfma_f32_32x32x16_bf16 v[80:95], v[246:249], v[116:119], v[80:95]
	ds_read_b128 v[10:13], v15 offset:8192
	s_waitcnt lgkmcnt(3)
	v_mfma_f32_32x32x16_bf16 v[96:111], v[250:253], v[120:123], v[96:111]
	v_add_u32_e32 v14, v0, v185
	ds_read_b128 v[246:249], v14
	s_waitcnt lgkmcnt(3)
	v_mfma_f32_32x32x16_bf16 v[80:95], v[2:5], v[120:123], v[80:95]
	ds_read_b128 v[250:253], v14 offset:8192
	s_waitcnt lgkmcnt(3)
	v_mfma_f32_32x32x16_bf16 v[96:111], v[6:9], v[124:127], v[96:111]
	v_add_u32_e32 v15, v0, v186
	ds_read_b128 v[2:5], v15
	s_waitcnt lgkmcnt(3)
	v_mfma_f32_32x32x16_bf16 v[80:95], v[10:13], v[124:127], v[80:95]
	ds_read_b128 v[6:9], v15 offset:8192
	s_waitcnt lgkmcnt(3)
	v_mfma_f32_32x32x16_bf16 v[96:111], v[246:249], v[128:131], v[96:111]
	v_add_u32_e32 v14, v0, v200
	ds_read_b128 v[10:13], v14
	s_waitcnt lgkmcnt(3)
	v_mfma_f32_32x32x16_bf16 v[80:95], v[250:253], v[128:131], v[80:95]
	ds_read_b128 v[246:249], v14 offset:8192
	s_waitcnt lgkmcnt(3)
	v_mfma_f32_32x32x16_bf16 v[96:111], v[2:5], v[132:135], v[96:111]
	v_add_u32_e32 v15, v0, v201
	ds_read_b128 v[250:253], v15
	s_waitcnt lgkmcnt(3)
	v_mfma_f32_32x32x16_bf16 v[80:95], v[6:9], v[132:135], v[80:95]
	ds_read_b128 v[2:5], v15 offset:8192
	s_waitcnt lgkmcnt(3)
	v_mfma_f32_32x32x16_bf16 v[96:111], v[10:13], v[136:139], v[96:111]
	s_waitcnt lgkmcnt(2)
	v_mfma_f32_32x32x16_bf16 v[80:95], v[246:249], v[136:139], v[80:95]
	s_waitcnt lgkmcnt(1)
	v_mfma_f32_32x32x16_bf16 v[96:111], v[250:253], v[140:143], v[96:111]
	s_waitcnt lgkmcnt(0)
	v_mfma_f32_32x32x16_bf16 v[80:95], v[2:5], v[140:143], v[80:95]
	s_cbranch_vccnz .LBB0_301
	v_add_u32_e32 v0, s59, v179
	v_add_u32_e32 v2, 32, v0
	v_cmp_le_i32_e32 vcc, v2, v172
	v_add_u32_e32 v2, 33, v0
	s_nop 6
	v_cndmask_b32_e32 v80, v195, v80, vcc
	v_cmp_lt_i32_e32 vcc, v0, v172
	s_nop 1
	v_cndmask_b32_e32 v97, v195, v97, vcc
	v_cmp_le_i32_e32 vcc, v0, v172
	s_nop 1
	v_cndmask_b32_e32 v96, v195, v96, vcc
	v_cmp_le_i32_e32 vcc, v2, v172
	v_add_u32_e32 v2, 2, v0
	s_nop 0
	v_cndmask_b32_e32 v81, v195, v81, vcc
	v_cmp_le_i32_e32 vcc, v2, v172
	v_add_u32_e32 v2, 34, v0
	s_nop 0
	v_cndmask_b32_e32 v98, v195, v98, vcc
	v_cmp_le_i32_e32 vcc, v2, v172
	v_add_u32_e32 v2, 3, v0
	s_nop 0
	v_cndmask_b32_e32 v82, v195, v82, vcc
	v_cmp_le_i32_e32 vcc, v2, v172
	v_add_u32_e32 v2, 35, v0
	s_nop 0
	v_cndmask_b32_e32 v99, v195, v99, vcc
	v_cmp_le_i32_e32 vcc, v2, v172
	v_add_u32_e32 v2, 8, v0
	s_nop 0
	v_cndmask_b32_e32 v83, v195, v83, vcc
	v_cmp_le_i32_e32 vcc, v2, v172
	v_add_u32_e32 v2, 40, v0
	s_nop 0
	v_cndmask_b32_e32 v100, v195, v100, vcc
	v_cmp_le_i32_e32 vcc, v2, v172
	v_add_u32_e32 v2, 9, v0
	s_nop 0
	v_cndmask_b32_e32 v84, v195, v84, vcc
	v_cmp_le_i32_e32 vcc, v2, v172
	v_add_u32_e32 v2, 41, v0
	s_nop 0
	v_cndmask_b32_e32 v101, v195, v101, vcc
	v_cmp_le_i32_e32 vcc, v2, v172
	v_add_u32_e32 v2, 10, v0
	s_nop 0
	v_cndmask_b32_e32 v85, v195, v85, vcc
	v_cmp_le_i32_e32 vcc, v2, v172
	v_add_u32_e32 v2, 42, v0
	s_nop 0
	v_cndmask_b32_e32 v102, v195, v102, vcc
	v_cmp_le_i32_e32 vcc, v2, v172
	v_add_u32_e32 v2, 11, v0
	s_nop 0
	v_cndmask_b32_e32 v86, v195, v86, vcc
	v_cmp_le_i32_e32 vcc, v2, v172
	v_add_u32_e32 v2, 43, v0
	s_nop 0
	v_cndmask_b32_e32 v103, v195, v103, vcc
	v_cmp_le_i32_e32 vcc, v2, v172
	v_add_u32_e32 v2, 16, v0
	s_nop 0
	v_cndmask_b32_e32 v87, v195, v87, vcc
	v_cmp_le_i32_e32 vcc, v2, v172
	v_add_u32_e32 v2, 48, v0
	s_nop 0
	v_cndmask_b32_e32 v104, v195, v104, vcc
	v_cmp_le_i32_e32 vcc, v2, v172
	v_add_u32_e32 v2, 17, v0
	s_nop 0
	v_cndmask_b32_e32 v88, v195, v88, vcc
	v_cmp_le_i32_e32 vcc, v2, v172
	v_add_u32_e32 v2, 49, v0
	s_nop 0
	v_cndmask_b32_e32 v105, v195, v105, vcc
	v_cmp_le_i32_e32 vcc, v2, v172
	v_add_u32_e32 v2, 18, v0
	s_nop 0
	v_cndmask_b32_e32 v89, v195, v89, vcc
	v_cmp_le_i32_e32 vcc, v2, v172
	v_add_u32_e32 v2, 50, v0
	s_nop 0
	v_cndmask_b32_e32 v106, v195, v106, vcc
	v_cmp_le_i32_e32 vcc, v2, v172
	v_add_u32_e32 v2, 19, v0
	s_nop 0
	v_cndmask_b32_e32 v90, v195, v90, vcc
	v_cmp_le_i32_e32 vcc, v2, v172
	v_add_u32_e32 v2, 51, v0
	s_nop 0
	v_cndmask_b32_e32 v107, v195, v107, vcc
	v_cmp_le_i32_e32 vcc, v2, v172
	v_add_u32_e32 v2, 24, v0
	s_nop 0
	v_cndmask_b32_e32 v91, v195, v91, vcc
	v_cmp_le_i32_e32 vcc, v2, v172
	v_add_u32_e32 v2, 56, v0
	s_nop 0
	v_cndmask_b32_e32 v108, v195, v108, vcc
	v_cmp_le_i32_e32 vcc, v2, v172
	v_add_u32_e32 v2, 25, v0
	s_nop 0
	v_cndmask_b32_e32 v92, v195, v92, vcc
	v_cmp_le_i32_e32 vcc, v2, v172
	v_add_u32_e32 v2, 57, v0
	s_nop 0
	v_cndmask_b32_e32 v109, v195, v109, vcc
	v_cmp_le_i32_e32 vcc, v2, v172
	v_add_u32_e32 v2, 26, v0
	s_nop 0
	v_cndmask_b32_e32 v93, v195, v93, vcc
	v_cmp_le_i32_e32 vcc, v2, v172
	v_add_u32_e32 v2, 58, v0
	s_nop 0
	v_cndmask_b32_e32 v110, v195, v110, vcc
	v_cmp_le_i32_e32 vcc, v2, v172
	v_add_u32_e32 v2, 27, v0
	v_add_u32_e32 v0, 59, v0
	v_cndmask_b32_e32 v94, v195, v94, vcc
	v_cmp_le_i32_e32 vcc, v2, v172
	s_nop 1
	v_cndmask_b32_e32 v111, v195, v111, vcc
	v_cmp_le_i32_e32 vcc, v0, v172
	s_nop 1
	v_cndmask_b32_e32 v95, v195, v95, vcc

.LBB0_303:
	v_sub_f32_e32 v8, v82, v2
	v_sub_f32_e32 v9, v83, v2
	v_sub_f32_e32 v7, v98, v2
	v_exp_f32_e32 v98, v8
	v_sub_f32_e32 v8, v99, v2
	v_exp_f32_e32 v99, v9
	v_sub_f32_e32 v9, v100, v2
	v_exp_f32_e32 v12, v9
	v_sub_f32_e32 v9, v84, v2
	v_exp_f32_e32 v100, v9
	v_sub_f32_e32 v9, v101, v2
	v_exp_f32_e32 v13, v9
	v_sub_f32_e32 v9, v85, v2
	v_exp_f32_e32 v101, v9
	v_sub_f32_e32 v9, v102, v2
	v_exp_f32_e32 v14, v9
	v_sub_f32_e32 v9, v86, v2
	v_exp_f32_e32 v102, v9
	v_sub_f32_e32 v9, v103, v2
	v_exp_f32_e32 v15, v9
	v_sub_f32_e32 v9, v87, v2
	v_sub_f32_e32 v3, v96, v2
	v_sub_f32_e32 v4, v80, v2
	v_exp_f32_e32 v103, v9
	v_sub_f32_e32 v9, v104, v2
	v_exp_f32_e32 v3, v3
	v_exp_f32_e32 v96, v4
	v_sub_f32_e32 v4, v97, v2
	v_sub_f32_e32 v5, v81, v2
	v_exp_f32_e32 v104, v9
	v_sub_f32_e32 v9, v88, v2
	v_exp_f32_e32 v4, v4
	v_exp_f32_e32 v97, v5
	v_exp_f32_e32 v88, v9
	v_sub_f32_e32 v9, v105, v2
	v_exp_f32_e32 v7, v7
	v_exp_f32_e32 v105, v9
	v_sub_f32_e32 v9, v89, v2
	v_exp_f32_e32 v8, v8
	v_exp_f32_e32 v89, v9
	v_sub_f32_e32 v9, v106, v2
	v_add_f32_e32 v5, v3, v96
	v_exp_f32_e32 v106, v9
	v_sub_f32_e32 v9, v90, v2
	v_add_f32_e32 v5, 0, v5
	v_add_f32_e32 v6, v4, v97
	v_exp_f32_e32 v90, v9
	v_sub_f32_e32 v9, v107, v2
	v_add_f32_e32 v5, v6, v5
	v_add_f32_e32 v6, v7, v98
	v_exp_f32_e32 v107, v9
	v_sub_f32_e32 v9, v91, v2
	v_add_f32_e32 v5, v6, v5
	v_add_f32_e32 v6, v8, v99
	v_exp_f32_e32 v91, v9
	v_sub_f32_e32 v9, v108, v2
	v_add_f32_e32 v5, v6, v5
	v_add_f32_e32 v6, v12, v100
	v_exp_f32_e32 v108, v9
	v_sub_f32_e32 v9, v92, v2
	v_add_f32_e32 v5, v6, v5
	v_add_f32_e32 v6, v13, v101
	v_exp_f32_e32 v92, v9
	v_sub_f32_e32 v9, v109, v2
	v_add_f32_e32 v5, v6, v5
	v_add_f32_e32 v6, v14, v102
	v_exp_f32_e32 v109, v9
	v_sub_f32_e32 v9, v93, v2
	v_add_f32_e32 v5, v6, v5
	v_add_f32_e32 v6, v15, v103
	v_exp_f32_e32 v93, v9
	v_sub_f32_e32 v9, v110, v2
	v_add_f32_e32 v5, v6, v5
	v_add_f32_e32 v6, v104, v88
	v_exp_f32_e32 v110, v9
	v_sub_f32_e32 v9, v94, v2
	v_add_f32_e32 v5, v6, v5
	v_add_f32_e32 v6, v105, v89
	v_exp_f32_e32 v94, v9
	v_sub_f32_e32 v9, v111, v2
	v_add_f32_e32 v5, v6, v5
	v_add_f32_e32 v6, v106, v90
	v_exp_f32_e32 v111, v9
	v_sub_f32_e32 v9, v95, v2
	v_add_f32_e32 v5, v6, v5
	v_add_f32_e32 v6, v107, v91
	v_exp_f32_e32 v95, v9
	v_add_f32_e32 v5, v6, v5
	v_add_f32_e32 v6, v108, v92
	v_add_f32_e32 v5, v6, v5
	v_add_f32_e32 v6, v109, v93
	v_add_f32_e32 v5, v6, v5
	v_add_f32_e32 v6, v110, v94
	v_add_f32_e32 v5, v6, v5
	v_add_f32_e32 v6, v111, v95
	v_add_f32_e32 v212, v6, v5
	v_fmac_f32_e32 v212, v211, v0
	s_add_i32 s2, s52, 0
	s_setprio 0
	v_add_u32_e32 v0, s2, v180
	v_add_u32_e32 v211, s2, v202
	v_cvt_pk_bf16_f32 v4, v3, v4
	v_add3_u32 v3, v0, v203, v202
	v_add3_u32 v86, v211, v204, v180
	v_cvt_pk_bf16_f32 v5, v7, v8
	ds_read_b64_tr_b16 v[8:9], v3 offset:32768
	ds_read_b64_tr_b16 v[10:11], v86 offset:34816
	v_cvt_pk_bf16_f32 v6, v12, v13
	v_cvt_pk_bf16_f32 v7, v14, v15
	ds_read_b64_tr_b16 v[12:13], v3 offset:36864
	ds_read_b64_tr_b16 v[80:81], v3 offset:40960
	ds_read_b64_tr_b16 v[84:85], v3 offset:45056
	ds_read_b64_tr_b16 v[14:15], v86 offset:38912
	ds_read_b64_tr_b16 v[82:83], v86 offset:43008
	ds_read_b64_tr_b16 v[86:87], v86 offset:47104
	s_waitcnt lgkmcnt(6)
	v_mfma_f32_32x32x16_bf16 v[64:79], v[8:11], v[4:7], v[64:79]
	v_cvt_pk_bf16_f32 v8, v104, v105
	v_cvt_pk_bf16_f32 v9, v106, v107
	v_cvt_pk_bf16_f32 v10, v108, v109
	v_cvt_pk_bf16_f32 v11, v110, v111
	v_add3_u32 v3, v0, v205, v202
	s_waitcnt lgkmcnt(2)
	v_mfma_f32_32x32x16_bf16 v[64:79], v[12:15], v[8:11], v[64:79]
	v_cvt_pk_bf16_f32 v12, v96, v97
	v_cvt_pk_bf16_f32 v13, v98, v99
	v_cvt_pk_bf16_f32 v14, v100, v101
	v_cvt_pk_bf16_f32 v15, v102, v103
	v_add3_u32 v100, v211, v206, v180
	s_waitcnt lgkmcnt(1)
	v_mfma_f32_32x32x16_bf16 v[64:79], v[80:83], v[12:15], v[64:79]
	v_cvt_pk_bf16_f32 v80, v88, v89
	ds_read_b64_tr_b16 v[88:89], v100 offset:34816
	v_cvt_pk_bf16_f32 v81, v90, v91
	v_cvt_pk_bf16_f32 v82, v92, v93
	v_cvt_pk_bf16_f32 v83, v94, v95
	s_waitcnt lgkmcnt(1)
	s_nop 0
	v_mfma_f32_32x32x16_bf16 v[64:79], v[84:87], v[80:83], v[64:79]
	ds_read_b64_tr_b16 v[86:87], v3 offset:32768
	ds_read_b64_tr_b16 v[90:91], v3 offset:36864
	ds_read_b64_tr_b16 v[94:95], v3 offset:40960
	ds_read_b64_tr_b16 v[98:99], v3 offset:45056
	ds_read_b64_tr_b16 v[92:93], v100 offset:38912
	ds_read_b64_tr_b16 v[96:97], v100 offset:43008
	ds_read_b64_tr_b16 v[100:101], v100 offset:47104
	v_add3_u32 v3, v0, v207, v202
	v_add3_u32 v0, v0, v209, v202
	s_waitcnt lgkmcnt(6)
	v_mfma_f32_32x32x16_bf16 v[48:63], v[86:89], v[4:7], v[48:63]
	s_waitcnt lgkmcnt(2)
	v_mfma_f32_32x32x16_bf16 v[48:63], v[90:93], v[8:11], v[48:63]
	s_waitcnt lgkmcnt(1)
	v_mfma_f32_32x32x16_bf16 v[48:63], v[94:97], v[12:15], v[48:63]
	s_waitcnt lgkmcnt(0)
	v_mfma_f32_32x32x16_bf16 v[48:63], v[98:101], v[80:83], v[48:63]
	v_add3_u32 v98, v211, v208, v180
	ds_read_b64_tr_b16 v[86:87], v98 offset:34816
	ds_read_b64_tr_b16 v[84:85], v3 offset:32768
	ds_read_b64_tr_b16 v[88:89], v3 offset:36864
	ds_read_b64_tr_b16 v[92:93], v3 offset:40960
	ds_read_b64_tr_b16 v[96:97], v3 offset:45056
	ds_read_b64_tr_b16 v[90:91], v98 offset:38912
	ds_read_b64_tr_b16 v[94:95], v98 offset:43008
	ds_read_b64_tr_b16 v[98:99], v98 offset:47104
	v_add3_u32 v3, v211, v210, v180
	v_mov_b32_e32 v211, v212
	s_waitcnt lgkmcnt(6)
	v_mfma_f32_32x32x16_bf16 v[32:47], v[84:87], v[4:7], v[32:47]
	s_waitcnt lgkmcnt(2)
	v_mfma_f32_32x32x16_bf16 v[32:47], v[88:91], v[8:11], v[32:47]
	s_waitcnt lgkmcnt(1)
	v_mfma_f32_32x32x16_bf16 v[32:47], v[92:95], v[12:15], v[32:47]
	s_waitcnt lgkmcnt(0)
	v_mfma_f32_32x32x16_bf16 v[32:47], v[96:99], v[80:83], v[32:47]
	ds_read_b64_tr_b16 v[86:87], v3 offset:34816
	ds_read_b64_tr_b16 v[84:85], v0 offset:32768
	ds_read_b64_tr_b16 v[88:89], v0 offset:36864
	ds_read_b64_tr_b16 v[92:93], v0 offset:40960
	ds_read_b64_tr_b16 v[96:97], v0 offset:45056
	ds_read_b64_tr_b16 v[90:91], v3 offset:38912
	ds_read_b64_tr_b16 v[94:95], v3 offset:43008
	ds_read_b64_tr_b16 v[98:99], v3 offset:47104
	s_waitcnt lgkmcnt(6)
	v_mfma_f32_32x32x16_bf16 v[16:31], v[84:87], v[4:7], v[16:31]
	s_waitcnt lgkmcnt(2)
	v_mfma_f32_32x32x16_bf16 v[16:31], v[88:91], v[8:11], v[16:31]
	s_waitcnt lgkmcnt(1)
	v_mfma_f32_32x32x16_bf16 v[16:31], v[92:95], v[12:15], v[16:31]
	s_waitcnt lgkmcnt(0)
	v_mfma_f32_32x32x16_bf16 v[16:31], v[96:99], v[80:83], v[16:31]
	s_add_i32 s59, s59, 64
	s_addk_i32 s58, 0x4000
	s_cmp_lg_u32 s56, s60
	s_cbranch_scc1 .LBB0_291

.LBB0_320:
	v_add_u32_e32 v155, s3, v8
	s_andn2_b64 vcc, exec, s[0:1]
	v_ashrrev_i32_e32 v154, s60, v155
	s_cbranch_vccnz .LBB0_395
	v_lshlrev_b32_e32 v160, 2, v156
	v_bfe_u32 v3, v6, 2, 2
	v_lshrrev_b32_e32 v8, 3, v6
	v_bfe_u32 v6, v6, 1, 1
	v_and_or_b32 v6, v8, 2, v6
	v_lshlrev_b32_e32 v8, 2, v3
	v_or_b32_e32 v3, v160, v3
	v_or_b32_e32 v9, v8, v156
	v_lshlrev_b32_e32 v170, 8, v3
	v_bitop3_b32 v3, v8, v6, v156 bitop3:0x36
	v_lshlrev_b32_e32 v10, 3, v152
	v_lshlrev_b32_e32 v172, 4, v3
	v_bitop3_b32 v3, v9, v6, 2 bitop3:0x36
	v_and_b32_e32 v161, 8, v10
	v_xor_b32_e32 v10, v156, v157
	v_lshlrev_b32_e32 v174, 4, v3
	v_or_b32_e32 v3, 4, v6
	v_lshlrev_b32_e32 v162, 4, v10
	v_bitop3_b32 v10, v156, v157, 2 bitop3:0x36
	v_bitop3_b32 v3, v9, v3, 2 bitop3:0x36
	v_lshlrev_b32_e32 v163, 4, v10
	v_bitop3_b32 v10, v156, v157, 4 bitop3:0x36
	v_lshlrev_b32_e32 v177, 4, v3
	v_or_b32_e32 v3, 8, v6
	v_lshlrev_b32_e32 v164, 4, v10
	v_bitop3_b32 v10, v156, v157, 6 bitop3:0x36
	v_bitop3_b32 v8, v6, v9, 4 bitop3:0x36
	v_bitop3_b32 v3, v9, v3, 2 bitop3:0x36
	v_lshlrev_b32_e32 v165, 4, v10
	v_bitop3_b32 v10, v156, v157, 8 bitop3:0x36
	v_lshlrev_b32_e32 v176, 4, v8
	v_bitop3_b32 v8, v6, v9, 8 bitop3:0x36
	v_lshlrev_b32_e32 v179, 4, v3
	v_or_b32_e32 v3, 12, v6
	v_bitop3_b32 v6, v6, v9, 12 bitop3:0x36
	s_add_i32 s75, s75, s3
	v_lshlrev_b32_e32 v166, 4, v10
	v_bitop3_b32 v10, v156, v157, 10 bitop3:0x36
	v_lshlrev_b32_e32 v180, 4, v6
	v_add_u32_e32 v6, s54, v153
	v_lshlrev_b32_e32 v167, 4, v10
	v_bitop3_b32 v10, v156, v157, 12 bitop3:0x36
	v_lshlrev_b32_e32 v178, 4, v8
	v_bitop3_b32 v3, v9, v3, 2 bitop3:0x36
	s_sub_i32 s0, s75, 59
	v_add_u32_e32 v8, 4, v6
	v_lshlrev_b32_e32 v168, 4, v10
	v_bitop3_b32 v10, v156, v157, 14 bitop3:0x36
	v_lshlrev_b32_e32 v181, 4, v3
	v_add_u32_e32 v3, s0, v4
	v_ashrrev_i32_e32 v9, 31, v8
	v_lshlrev_b32_e32 v169, 4, v10
	v_sub_u32_e32 v3, v3, v160
	v_lshl_add_u64 v[8:9], v[8:9], 0, s[52:53]
	v_mov_b64_e32 v[10:11], s[20:21]
	v_subrev_u32_e32 v182, s52, v3
	v_mad_u64_u32 v[12:13], s[0:1], v8, s62, v[10:11]
	v_and_b32_e32 v3, 15, v7
	v_mad_i32_i24 v13, v9, s62, v13
	v_lshlrev_b32_e32 v8, 4, v3
	v_mov_b32_e32 v3, v1
	v_lshl_add_u64 v[2:3], v[12:13], 0, v[2:3]
	v_ashrrev_i32_e32 v7, 31, v6
	v_lshl_add_u64 v[146:147], s[18:19], 0, v[2:3]
	v_lshl_add_u64 v[2:3], v[6:7], 0, s[52:53]
	v_mad_u64_u32 v[6:7], s[0:1], v2, s62, v[10:11]
	v_and_b32_e32 v2, 15, v5
	v_mad_i32_i24 v7, v3, s62, v7
	v_lshlrev_b32_e32 v2, 4, v2
	v_mov_b32_e32 v3, v1
	v_mov_b32_e32 v9, v1
	v_lshl_add_u64 v[2:3], v[6:7], 0, v[2:3]
	v_lshl_add_u64 v[8:9], v[12:13], 0, v[8:9]
	v_lshl_add_u64 v[148:149], s[14:15], 0, v[2:3]
	v_lshl_add_u64 v[2:3], v[6:7], 0, v[0:1]
	v_mov_b32_e32 v14, v1
	v_mov_b32_e32 v15, v1
	v_lshl_add_u64 v[144:145], s[14:15], 0, v[8:9]
	v_lshl_add_u64 v[150:151], s[18:19], 0, v[2:3]
	v_mov_b32_e32 v0, v1
	v_mov_b32_e32 v2, v1
	v_mov_b32_e32 v3, v1
	v_mov_b32_e32 v4, v1
	v_mov_b32_e32 v5, v1
	v_mov_b32_e32 v6, v1
	v_mov_b32_e32 v7, v1
	v_mov_b32_e32 v8, v1
	v_mov_b32_e32 v9, v1
	v_mov_b32_e32 v10, v1
	v_mov_b32_e32 v11, v1
	v_mov_b32_e32 v12, v1
	v_mov_b32_e32 v13, v1
	v_mov_b64_e32 v[78:79], v[14:15]
	v_mov_b64_e32 v[62:63], v[14:15]
	v_mov_b64_e32 v[46:47], v[14:15]
	v_mov_b64_e32 v[30:31], v[14:15]
	s_or_b32 s97, s75, 31
	s_add_i32 s96, s75, 0xffffff80
	s_ashr_i32 s76, s75, s60
	v_add_u32_e32 v159, 0, v158
	s_mov_b32 s66, 1
	s_mov_b32 s3, s21
	s_mov_b32 s20, 0
	v_mov_b32_e32 v183, 0
	v_mov_b32_e32 v184, 0xf149f2ca
	v_mov_b64_e32 v[76:77], v[12:13]
	v_mov_b64_e32 v[74:75], v[10:11]
	v_mov_b64_e32 v[72:73], v[8:9]
	v_mov_b64_e32 v[70:71], v[6:7]
	v_mov_b64_e32 v[68:69], v[4:5]
	v_mov_b64_e32 v[66:67], v[2:3]
	v_mov_b64_e32 v[64:65], v[0:1]
	v_mov_b64_e32 v[60:61], v[12:13]
	v_mov_b64_e32 v[58:59], v[10:11]
	v_mov_b64_e32 v[56:57], v[8:9]
	v_mov_b64_e32 v[54:55], v[6:7]
	v_mov_b64_e32 v[52:53], v[4:5]
	v_mov_b64_e32 v[50:51], v[2:3]
	v_mov_b64_e32 v[48:49], v[0:1]
	v_mov_b64_e32 v[44:45], v[12:13]
	v_mov_b64_e32 v[42:43], v[10:11]
	v_mov_b64_e32 v[40:41], v[8:9]
	v_mov_b64_e32 v[38:39], v[6:7]
	v_mov_b64_e32 v[36:37], v[4:5]
	v_mov_b64_e32 v[34:35], v[2:3]
	v_mov_b64_e32 v[32:33], v[0:1]
	v_mov_b64_e32 v[28:29], v[12:13]
	v_mov_b64_e32 v[26:27], v[10:11]
	v_mov_b64_e32 v[24:25], v[8:9]
	v_mov_b64_e32 v[22:23], v[6:7]
	v_mov_b64_e32 v[20:21], v[4:5]
	v_mov_b64_e32 v[18:19], v[2:3]
	v_mov_b64_e32 v[16:17], v[0:1]
	s_lshl_b32 s0, 1, s60
	s_add_i32 s0, s0, -1
	v_and_b32_e32 v254, s0, v155
	v_min_u32_e32 v254, 0x80, v254
	s_waitcnt vmcnt(0)

.LBB0_324:
	s_cmp_le_i32 s52, s97
	s_cselect_b64 s[0:1], -1, 0
	s_add_i32 s53, s52, 63
	s_cmp_ge_i32 s53, s96
	s_cselect_b64 s[56:57], -1, 0
	s_and_b64 s[0:1], s[0:1], s[56:57]
	s_lshr_b32 s53, s52, s60
	s_cmp_eq_u32 s53, s76
	s_cselect_b64 s[56:57], -1, 0
	s_and_b64 s[0:1], s[0:1], s[56:57]
	s_andn2_b64 vcc, exec, s[0:1]
	s_cbranch_vccnz .LBB0_392
	s_and_b32 s53, s20, 0x4000
	v_add_u32_e32 v0, s53, v159
	v_add_u32_e32 v14, v0, v162
	ds_read_b128 v[2:5], v14
	ds_read_b128 v[6:9], v14 offset:8192
	v_add_u32_e32 v15, v0, v163
	ds_read_b128 v[10:13], v15
	ds_read_b128 v[246:249], v15 offset:8192
	s_waitcnt lgkmcnt(3)
	v_mfma_f32_32x32x16_bf16 v[96:111], v[2:5], v[112:115], 0
	v_add_u32_e32 v14, v0, v164
	ds_read_b128 v[250:253], v14
	s_waitcnt lgkmcnt(3)
	v_mfma_f32_32x32x16_bf16 v[80:95], v[6:9], v[112:115], 0
	ds_read_b128 v[2:5], v14 offset:8192
	s_waitcnt lgkmcnt(3)
	v_mfma_f32_32x32x16_bf16 v[96:111], v[10:13], v[116:119], v[96:111]
	v_add_u32_e32 v15, v0, v165
	ds_read_b128 v[6:9], v15
	s_waitcnt lgkmcnt(3)
	v_mfma_f32_32x32x16_bf16 v[80:95], v[246:249], v[116:119], v[80:95]
	ds_read_b128 v[10:13], v15 offset:8192
	s_waitcnt lgkmcnt(3)
	v_mfma_f32_32x32x16_bf16 v[96:111], v[250:253], v[120:123], v[96:111]
	v_add_u32_e32 v14, v0, v166
	ds_read_b128 v[246:249], v14
	s_waitcnt lgkmcnt(3)
	v_mfma_f32_32x32x16_bf16 v[80:95], v[2:5], v[120:123], v[80:95]
	ds_read_b128 v[250:253], v14 offset:8192
	s_waitcnt lgkmcnt(3)
	v_mfma_f32_32x32x16_bf16 v[96:111], v[6:9], v[124:127], v[96:111]
	v_add_u32_e32 v15, v0, v167
	ds_read_b128 v[2:5], v15
	s_waitcnt lgkmcnt(3)
	v_mfma_f32_32x32x16_bf16 v[80:95], v[10:13], v[124:127], v[80:95]
	ds_read_b128 v[6:9], v15 offset:8192
	s_waitcnt lgkmcnt(3)
	v_mfma_f32_32x32x16_bf16 v[96:111], v[246:249], v[128:131], v[96:111]
	v_add_u32_e32 v14, v0, v168
	ds_read_b128 v[10:13], v14
	s_waitcnt lgkmcnt(3)
	v_mfma_f32_32x32x16_bf16 v[80:95], v[250:253], v[128:131], v[80:95]
	ds_read_b128 v[246:249], v14 offset:8192
	s_waitcnt lgkmcnt(3)
	v_mfma_f32_32x32x16_bf16 v[96:111], v[2:5], v[132:135], v[96:111]
	v_add_u32_e32 v15, v0, v169
	ds_read_b128 v[250:253], v15
	s_waitcnt lgkmcnt(3)
	v_mfma_f32_32x32x16_bf16 v[80:95], v[6:9], v[132:135], v[80:95]
	ds_read_b128 v[2:5], v15 offset:8192
	s_waitcnt lgkmcnt(3)
	v_mfma_f32_32x32x16_bf16 v[96:111], v[10:13], v[136:139], v[96:111]
	s_waitcnt lgkmcnt(2)
	v_mfma_f32_32x32x16_bf16 v[80:95], v[246:249], v[136:139], v[80:95]
	s_waitcnt lgkmcnt(1)
	v_mfma_f32_32x32x16_bf16 v[96:111], v[250:253], v[140:143], v[96:111]
	s_waitcnt lgkmcnt(0)
	v_mfma_f32_32x32x16_bf16 v[80:95], v[2:5], v[140:143], v[80:95]
	s_nop 7
	s_nop 3
	v_add_u32_e32 v0, 59, v182
	v_subrev_u32_e32 v246, 0, v0
	v_subrev_u32_e32 v247, 1, v0
	v_subrev_u32_e32 v248, 2, v0
	v_cmp_ge_u32_e64 vcc, v254, v246
	v_cmp_ge_u32_e64 s[0:1], v254, v247
	v_cmp_ge_u32_e64 s[56:57], v254, v248
	v_cndmask_b32_e64 v13, v195, v96, vcc
	v_cndmask_b32_e64 v97, v195, v97, s[0:1]
	v_cndmask_b32_e64 v14, v195, v98, s[56:57]
	v_subrev_u32_e32 v246, 3, v0
	v_subrev_u32_e32 v247, 8, v0
	v_subrev_u32_e32 v248, 9, v0
	v_cmp_ge_u32_e64 vcc, v254, v246
	v_cmp_ge_u32_e64 s[0:1], v254, v247
	v_cmp_ge_u32_e64 s[56:57], v254, v248
	v_cndmask_b32_e64 v98, v195, v99, vcc
	v_cndmask_b32_e64 v11, v195, v100, s[0:1]
	v_cndmask_b32_e64 v15, v195, v101, s[56:57]
	v_subrev_u32_e32 v246, 10, v0
	v_subrev_u32_e32 v247, 11, v0
	v_subrev_u32_e32 v248, 16, v0
	v_cmp_ge_u32_e64 vcc, v254, v246
	v_cmp_ge_u32_e64 s[0:1], v254, v247
	v_cmp_ge_u32_e64 s[56:57], v254, v248
	v_cndmask_b32_e64 v9, v195, v102, vcc
	v_cndmask_b32_e64 v12, v195, v103, s[0:1]
	v_cndmask_b32_e64 v7, v195, v104, s[56:57]
	v_subrev_u32_e32 v246, 17, v0
	v_subrev_u32_e32 v247, 18, v0
	v_subrev_u32_e32 v248, 19, v0
	v_cmp_ge_u32_e64 vcc, v254, v246
	v_cmp_ge_u32_e64 s[0:1], v254, v247
	v_cmp_ge_u32_e64 s[56:57], v254, v248
	v_cndmask_b32_e64 v10, v195, v105, vcc
	v_cndmask_b32_e64 v5, v195, v106, s[0:1]
	v_cndmask_b32_e64 v8, v195, v107, s[56:57]
	v_subrev_u32_e32 v246, 24, v0
	v_subrev_u32_e32 v247, 25, v0
	v_subrev_u32_e32 v248, 26, v0
	v_cmp_ge_u32_e64 vcc, v254, v246
	v_cmp_ge_u32_e64 s[0:1], v254, v247
	v_cmp_ge_u32_e64 s[56:57], v254, v248
	v_cndmask_b32_e64 v3, v195, v108, vcc
	v_cndmask_b32_e64 v6, v195, v109, s[0:1]
	v_cndmask_b32_e64 v2, v195, v110, s[56:57]
	v_subrev_u32_e32 v246, 27, v0
	v_subrev_u32_e32 v247, 32, v0
	v_subrev_u32_e32 v248, 33, v0
	v_cmp_ge_u32_e64 vcc, v254, v246
	v_cmp_ge_u32_e64 s[0:1], v254, v247
	v_cmp_ge_u32_e64 s[56:57], v254, v248
	v_cndmask_b32_e64 v4, v195, v111, vcc
	v_cndmask_b32_e64 v80, v195, v80, s[0:1]
	v_cndmask_b32_e64 v81, v195, v81, s[56:57]
	v_subrev_u32_e32 v246, 34, v0
	v_subrev_u32_e32 v247, 35, v0
	v_subrev_u32_e32 v248, 40, v0
	v_cmp_ge_u32_e64 vcc, v254, v246
	v_cmp_ge_u32_e64 s[0:1], v254, v247
	v_cmp_ge_u32_e64 s[56:57], v254, v248
	v_cndmask_b32_e64 v82, v195, v82, vcc
	v_cndmask_b32_e64 v83, v195, v83, s[0:1]
	v_cndmask_b32_e64 v84, v195, v84, s[56:57]
	v_subrev_u32_e32 v246, 41, v0
	v_subrev_u32_e32 v247, 42, v0
	v_subrev_u32_e32 v248, 43, v0
	v_cmp_ge_u32_e64 vcc, v254, v246
	v_cmp_ge_u32_e64 s[0:1], v254, v247
	v_cmp_ge_u32_e64 s[56:57], v254, v248
	v_cndmask_b32_e64 v85, v195, v85, vcc
	v_cndmask_b32_e64 v86, v195, v86, s[0:1]
	v_cndmask_b32_e64 v87, v195, v87, s[56:57]
	v_subrev_u32_e32 v246, 48, v0
	v_subrev_u32_e32 v247, 49, v0
	v_subrev_u32_e32 v248, 50, v0
	v_cmp_ge_u32_e64 vcc, v254, v246
	v_cmp_ge_u32_e64 s[0:1], v254, v247
	v_cmp_ge_u32_e64 s[56:57], v254, v248
	v_cndmask_b32_e64 v88, v195, v88, vcc
	v_cndmask_b32_e64 v89, v195, v89, s[0:1]
	v_cndmask_b32_e64 v90, v195, v90, s[56:57]
	v_subrev_u32_e32 v246, 51, v0
	v_subrev_u32_e32 v247, 56, v0
	v_subrev_u32_e32 v248, 57, v0
	v_cmp_ge_u32_e64 vcc, v254, v246
	v_cmp_ge_u32_e64 s[0:1], v254, v247
	v_cmp_ge_u32_e64 s[56:57], v254, v248
	v_cndmask_b32_e64 v91, v195, v91, vcc
	v_cndmask_b32_e64 v92, v195, v92, s[0:1]
	v_cndmask_b32_e64 v93, v195, v93, s[56:57]
	v_subrev_u32_e32 v246, 58, v0
	v_subrev_u32_e32 v247, 59, v0
	v_cmp_ge_u32_e64 vcc, v254, v246
	v_cmp_ge_u32_e64 s[0:1], v254, v247
	s_nop 1
	v_cndmask_b32_e64 v94, v195, v94, vcc
	v_cndmask_b32_e64 v95, v195, v95, s[0:1]
	s_setprio 1
	v_max_f32_e32 v0, v13, v13
	v_max_f32_e32 v96, v97, v97
	v_max_f32_e32 v0, v0, v96
	v_max3_f32 v0, v0, v14, v98
	v_max3_f32 v0, v0, v11, v15
	v_max3_f32 v0, v0, v9, v12
	v_max3_f32 v0, v0, v7, v10
	v_max3_f32 v0, v0, v5, v8
	v_max3_f32 v0, v0, v3, v6
	v_max3_f32 v0, v0, v2, v4
	v_max3_f32 v0, v0, v80, v81
	v_max3_f32 v0, v0, v82, v83
	v_max3_f32 v0, v0, v84, v85
	v_max3_f32 v0, v0, v86, v87
	v_max3_f32 v0, v0, v88, v89
	v_max3_f32 v0, v0, v90, v91
	v_max3_f32 v0, v0, v92, v93
	v_max3_f32 v0, v0, v94, v95
	v_mov_b32_e32 v96, v0
	s_nop 1
	v_permlane32_swap_b32_e32 v0, v96
	v_max3_f32 v96, v184, v0, v96
	v_sub_f32_e32 v0, v184, v96
	v_exp_f32_e32 v0, v0
	s_nop 0
	v_cmp_neq_f32_e32 vcc, 1.0, v0
	s_cbranch_vccz .LBB0_391
	v_pk_mul_f32 v[78:79], v[78:79], v[0:1] op_sel_hi:[1,0]
	v_pk_mul_f32 v[76:77], v[76:77], v[0:1] op_sel_hi:[1,0]
	v_pk_mul_f32 v[74:75], v[74:75], v[0:1] op_sel_hi:[1,0]
	v_pk_mul_f32 v[72:73], v[72:73], v[0:1] op_sel_hi:[1,0]
	v_pk_mul_f32 v[70:71], v[70:71], v[0:1] op_sel_hi:[1,0]
	v_pk_mul_f32 v[68:69], v[68:69], v[0:1] op_sel_hi:[1,0]
	v_pk_mul_f32 v[66:67], v[66:67], v[0:1] op_sel_hi:[1,0]
	v_pk_mul_f32 v[64:65], v[64:65], v[0:1] op_sel_hi:[1,0]
	v_pk_mul_f32 v[62:63], v[62:63], v[0:1] op_sel_hi:[1,0]
	v_pk_mul_f32 v[60:61], v[60:61], v[0:1] op_sel_hi:[1,0]
	v_pk_mul_f32 v[58:59], v[58:59], v[0:1] op_sel_hi:[1,0]
	v_pk_mul_f32 v[56:57], v[56:57], v[0:1] op_sel_hi:[1,0]
	v_pk_mul_f32 v[54:55], v[54:55], v[0:1] op_sel_hi:[1,0]
	v_pk_mul_f32 v[52:53], v[52:53], v[0:1] op_sel_hi:[1,0]
	v_pk_mul_f32 v[50:51], v[50:51], v[0:1] op_sel_hi:[1,0]
	v_pk_mul_f32 v[48:49], v[48:49], v[0:1] op_sel_hi:[1,0]
	v_pk_mul_f32 v[46:47], v[46:47], v[0:1] op_sel_hi:[1,0]
	v_pk_mul_f32 v[44:45], v[44:45], v[0:1] op_sel_hi:[1,0]
	v_pk_mul_f32 v[42:43], v[42:43], v[0:1] op_sel_hi:[1,0]
	v_pk_mul_f32 v[40:41], v[40:41], v[0:1] op_sel_hi:[1,0]
	v_pk_mul_f32 v[38:39], v[38:39], v[0:1] op_sel_hi:[1,0]
	v_pk_mul_f32 v[36:37], v[36:37], v[0:1] op_sel_hi:[1,0]
	v_pk_mul_f32 v[34:35], v[34:35], v[0:1] op_sel_hi:[1,0]
	v_pk_mul_f32 v[32:33], v[32:33], v[0:1] op_sel_hi:[1,0]
	v_pk_mul_f32 v[30:31], v[30:31], v[0:1] op_sel_hi:[1,0]
	v_pk_mul_f32 v[28:29], v[28:29], v[0:1] op_sel_hi:[1,0]
	v_pk_mul_f32 v[26:27], v[26:27], v[0:1] op_sel_hi:[1,0]
	v_pk_mul_f32 v[24:25], v[24:25], v[0:1] op_sel_hi:[1,0]
	v_pk_mul_f32 v[22:23], v[22:23], v[0:1] op_sel_hi:[1,0]
	v_pk_mul_f32 v[20:21], v[20:21], v[0:1] op_sel_hi:[1,0]
	v_pk_mul_f32 v[18:19], v[18:19], v[0:1] op_sel_hi:[1,0]
	v_pk_mul_f32 v[16:17], v[16:17], v[0:1] op_sel_hi:[1,0]
.LBB0_391:
	v_sub_f32_e32 v13, v13, v96
	v_sub_f32_e32 v80, v80, v96
	v_exp_f32_e32 v13, v13
	v_exp_f32_e32 v99, v80
	v_sub_f32_e32 v80, v97, v96
	v_sub_f32_e32 v81, v81, v96
	v_exp_f32_e32 v80, v80
	v_exp_f32_e32 v97, v81
	v_add_f32_e32 v81, v99, v13
	v_sub_f32_e32 v14, v14, v96
	v_sub_f32_e32 v82, v82, v96
	v_add_f32_e32 v81, 0, v81
	v_add_f32_e32 v100, v97, v80
	v_exp_f32_e32 v14, v14
	v_exp_f32_e32 v101, v82
	v_sub_f32_e32 v82, v98, v96
	v_sub_f32_e32 v83, v83, v96
	v_sub_f32_e32 v84, v84, v96
	v_exp_f32_e32 v82, v82
	v_exp_f32_e32 v98, v83
	v_add_f32_e32 v81, v100, v81
	v_sub_f32_e32 v11, v11, v96
	v_exp_f32_e32 v100, v84
	v_sub_f32_e32 v84, v85, v96
	v_sub_f32_e32 v9, v9, v96
	v_exp_f32_e32 v11, v11
	v_sub_f32_e32 v15, v15, v96
	v_exp_f32_e32 v102, v84
	v_exp_f32_e32 v84, v9
	v_sub_f32_e32 v9, v86, v96
	v_exp_f32_e32 v15, v15
	v_exp_f32_e32 v103, v9
	v_sub_f32_e32 v9, v12, v96
	v_sub_f32_e32 v7, v7, v96
	v_add_f32_e32 v83, v101, v14
	v_exp_f32_e32 v12, v9
	v_sub_f32_e32 v9, v87, v96
	v_exp_f32_e32 v105, v7
	v_sub_f32_e32 v7, v88, v96
	v_add_f32_e32 v81, v83, v81
	v_add_f32_e32 v83, v98, v82
	v_exp_f32_e32 v104, v9
	v_exp_f32_e32 v88, v7
	v_sub_f32_e32 v7, v10, v96
	v_sub_f32_e32 v5, v5, v96
	v_add_f32_e32 v81, v83, v81
	v_add_f32_e32 v83, v100, v11
	v_exp_f32_e32 v106, v7
	v_sub_f32_e32 v7, v89, v96
	v_exp_f32_e32 v107, v5
	v_sub_f32_e32 v5, v90, v96
	v_add_f32_e32 v81, v83, v81
	v_add_f32_e32 v83, v102, v15
	v_exp_f32_e32 v89, v7
	v_exp_f32_e32 v90, v5
	v_sub_f32_e32 v5, v8, v96
	v_sub_f32_e32 v3, v3, v96
	v_add_f32_e32 v9, v83, v81
	v_add_f32_e32 v81, v103, v84
	v_exp_f32_e32 v108, v5
	v_sub_f32_e32 v5, v91, v96
	v_exp_f32_e32 v109, v3
	v_sub_f32_e32 v3, v92, v96
	v_add_f32_e32 v9, v81, v9
	v_add_f32_e32 v81, v104, v12
	v_exp_f32_e32 v91, v5
	v_exp_f32_e32 v92, v3
	v_sub_f32_e32 v3, v6, v96
	v_sub_f32_e32 v2, v2, v96
	v_add_f32_e32 v7, v81, v9
	v_add_f32_e32 v9, v88, v105
	v_exp_f32_e32 v110, v3
	v_sub_f32_e32 v3, v93, v96
	v_exp_f32_e32 v111, v2
	v_sub_f32_e32 v2, v94, v96
	v_add_f32_e32 v7, v9, v7
	v_add_f32_e32 v9, v89, v106
	v_exp_f32_e32 v93, v3
	v_exp_f32_e32 v94, v2
	v_sub_f32_e32 v2, v4, v96
	v_add_f32_e32 v5, v9, v7
	v_add_f32_e32 v7, v90, v107
	v_exp_f32_e32 v184, v2
	v_sub_f32_e32 v2, v95, v96
	v_add_f32_e32 v5, v7, v5
	v_add_f32_e32 v7, v91, v108
	v_exp_f32_e32 v95, v2
	v_add_f32_e32 v3, v7, v5
	v_add_f32_e32 v5, v92, v109
	v_add_f32_e32 v3, v5, v3
	v_add_f32_e32 v5, v93, v110
	v_add_f32_e32 v2, v5, v3
	v_add_f32_e32 v3, v94, v111
	v_add_f32_e32 v2, v3, v2
	v_add_f32_e32 v3, v95, v184
	v_add_f32_e32 v185, v3, v2
	v_fmac_f32_e32 v185, v183, v0
	s_add_i32 s0, s53, 0
	s_setprio 0
	v_cvt_pk_bf16_f32 v3, v14, v82
	v_add_u32_e32 v0, s0, v161
	v_add_u32_e32 v14, s0, v170
	v_cvt_pk_bf16_f32 v2, v13, v80
	v_add3_u32 v13, v0, v172, v170
	v_add3_u32 v86, v14, v174, v161
	ds_read_b64_tr_b16 v[6:7], v13 offset:32768
	ds_read_b64_tr_b16 v[8:9], v86 offset:34816
	v_cvt_pk_bf16_f32 v4, v11, v15
	v_cvt_pk_bf16_f32 v5, v84, v12
	ds_read_b64_tr_b16 v[10:11], v13 offset:36864
	ds_read_b64_tr_b16 v[80:81], v13 offset:40960
	ds_read_b64_tr_b16 v[84:85], v13 offset:45056
	ds_read_b64_tr_b16 v[12:13], v86 offset:38912
	ds_read_b64_tr_b16 v[82:83], v86 offset:43008
	ds_read_b64_tr_b16 v[86:87], v86 offset:47104
	s_waitcnt lgkmcnt(6)
	v_mfma_f32_32x32x16_bf16 v[64:79], v[6:9], v[2:5], v[64:79]
	v_cvt_pk_bf16_f32 v6, v105, v106
	v_cvt_pk_bf16_f32 v7, v107, v108
	v_cvt_pk_bf16_f32 v8, v109, v110
	v_cvt_pk_bf16_f32 v9, v111, v184
	v_add3_u32 v15, v0, v176, v170
	v_mov_b32_e32 v183, v185
	s_waitcnt lgkmcnt(2)
	v_mfma_f32_32x32x16_bf16 v[64:79], v[10:13], v[6:9], v[64:79]
	v_cvt_pk_bf16_f32 v10, v99, v97
	v_cvt_pk_bf16_f32 v11, v101, v98
	v_cvt_pk_bf16_f32 v12, v100, v102
	v_cvt_pk_bf16_f32 v13, v103, v104
	v_add3_u32 v97, v14, v179, v161
	s_waitcnt lgkmcnt(1)
	v_mfma_f32_32x32x16_bf16 v[64:79], v[80:83], v[10:13], v[64:79]
	v_cvt_pk_bf16_f32 v83, v94, v95
	v_add3_u32 v94, v14, v177, v161
	v_cvt_pk_bf16_f32 v80, v88, v89
	ds_read_b64_tr_b16 v[88:89], v94 offset:34816
	v_cvt_pk_bf16_f32 v81, v90, v91
	v_cvt_pk_bf16_f32 v82, v92, v93
	v_add3_u32 v14, v14, v181, v161
	s_waitcnt lgkmcnt(1)
	v_mfma_f32_32x32x16_bf16 v[64:79], v[84:87], v[80:83], v[64:79]
	ds_read_b64_tr_b16 v[86:87], v15 offset:32768
	ds_read_b64_tr_b16 v[90:91], v15 offset:36864
	ds_read_b64_tr_b16 v[98:99], v15 offset:40960
	ds_read_b64_tr_b16 v[102:103], v15 offset:45056
	ds_read_b64_tr_b16 v[92:93], v94 offset:38912
	ds_read_b64_tr_b16 v[100:101], v94 offset:43008
	ds_read_b64_tr_b16 v[104:105], v94 offset:47104
	v_add3_u32 v15, v0, v178, v170
	v_add3_u32 v0, v0, v180, v170
	s_waitcnt lgkmcnt(6)
	v_mfma_f32_32x32x16_bf16 v[48:63], v[86:89], v[2:5], v[48:63]
	s_waitcnt lgkmcnt(2)
	v_mfma_f32_32x32x16_bf16 v[48:63], v[90:93], v[6:9], v[48:63]
	s_waitcnt lgkmcnt(1)
	v_mfma_f32_32x32x16_bf16 v[48:63], v[98:101], v[10:13], v[48:63]
	ds_read_b64_tr_b16 v[86:87], v97 offset:34816
	ds_read_b64_tr_b16 v[84:85], v15 offset:32768
	ds_read_b64_tr_b16 v[88:89], v15 offset:36864
	ds_read_b64_tr_b16 v[92:93], v15 offset:40960
	ds_read_b64_tr_b16 v[98:99], v15 offset:45056
	ds_read_b64_tr_b16 v[90:91], v97 offset:38912
	ds_read_b64_tr_b16 v[94:95], v97 offset:43008
	ds_read_b64_tr_b16 v[100:101], v97 offset:47104
	s_waitcnt lgkmcnt(6)
	v_mfma_f32_32x32x16_bf16 v[32:47], v[84:87], v[2:5], v[32:47]
	s_waitcnt lgkmcnt(2)
	v_mfma_f32_32x32x16_bf16 v[32:47], v[88:91], v[6:9], v[32:47]
	s_waitcnt lgkmcnt(1)
	v_mfma_f32_32x32x16_bf16 v[32:47], v[92:95], v[10:13], v[32:47]
	s_waitcnt lgkmcnt(0)
	v_mfma_f32_32x32x16_bf16 v[32:47], v[98:101], v[80:83], v[32:47]
	ds_read_b64_tr_b16 v[86:87], v14 offset:34816
	ds_read_b64_tr_b16 v[84:85], v0 offset:32768
	ds_read_b64_tr_b16 v[88:89], v0 offset:36864
	ds_read_b64_tr_b16 v[92:93], v0 offset:40960
	ds_read_b64_tr_b16 v[98:99], v0 offset:45056
	ds_read_b64_tr_b16 v[90:91], v14 offset:38912
	ds_read_b64_tr_b16 v[94:95], v14 offset:43008
	ds_read_b64_tr_b16 v[100:101], v14 offset:47104
	s_waitcnt lgkmcnt(6)
	v_mfma_f32_32x32x16_bf16 v[16:31], v[84:87], v[2:5], v[16:31]
	s_waitcnt lgkmcnt(2)
	v_mfma_f32_32x32x16_bf16 v[16:31], v[88:91], v[6:9], v[16:31]
	s_waitcnt lgkmcnt(1)
	v_mfma_f32_32x32x16_bf16 v[16:31], v[92:95], v[10:13], v[16:31]
	v_mfma_f32_32x32x16_bf16 v[48:63], v[102:105], v[80:83], v[48:63]
	s_waitcnt lgkmcnt(0)
	v_mfma_f32_32x32x16_bf16 v[16:31], v[98:101], v[80:83], v[16:31]
	s_branch .LBB0_393

.LBB0_431:
	s_and_b32 s2, s55, 0x4000
	v_add_u32_e32 v0, s2, v179
	v_add_u32_e32 v14, v0, v182
	ds_read_b128 v[2:5], v14
	ds_read_b128 v[6:9], v14 offset:8192
	v_add_u32_e32 v15, v0, v183
	ds_read_b128 v[10:13], v15
	ds_read_b128 v[246:249], v15 offset:8192
	v_mov_b32_e32 v81, v80
	v_mov_b32_e32 v82, v80
	v_mov_b32_e32 v83, v80
	v_mov_b32_e32 v84, v80
	v_mov_b32_e32 v85, v80
	v_mov_b32_e32 v86, v80
	v_mov_b32_e32 v87, v80
	v_mov_b32_e32 v88, v80
	v_mov_b32_e32 v89, v80
	v_mov_b32_e32 v90, v80
	v_mov_b32_e32 v91, v80
	v_mov_b32_e32 v92, v80
	v_mov_b32_e32 v93, v80
	v_mov_b32_e32 v94, v80
	v_mov_b32_e32 v95, v80
	s_andn2_b64 vcc, exec, s[0:1]
	s_waitcnt lgkmcnt(3)
	v_mfma_f32_32x32x16_bf16 v[96:111], v[2:5], v[112:115], v[80:95]
	v_add_u32_e32 v14, v0, v184
	ds_read_b128 v[250:253], v14
	s_waitcnt lgkmcnt(3)
	v_mfma_f32_32x32x16_bf16 v[80:95], v[6:9], v[112:115], v[80:95]
	ds_read_b128 v[2:5], v14 offset:8192
	s_waitcnt lgkmcnt(3)
	v_mfma_f32_32x32x16_bf16 v[96:111], v[10:13], v[116:119], v[96:111]
	v_add_u32_e32 v15, v0, v185
	ds_read_b128 v[6:9], v15
	s_waitcnt lgkmcnt(3)
	v_mfma_f32_32x32x16_bf16 v[80:95], v[246:249], v[116:119], v[80:95]
	ds_read_b128 v[10:13], v15 offset:8192
	s_waitcnt lgkmcnt(3)
	v_mfma_f32_32x32x16_bf16 v[96:111], v[250:253], v[120:123], v[96:111]
	v_add_u32_e32 v14, v0, v186
	ds_read_b128 v[246:249], v14
	s_waitcnt lgkmcnt(3)
	v_mfma_f32_32x32x16_bf16 v[80:95], v[2:5], v[120:123], v[80:95]
	ds_read_b128 v[250:253], v14 offset:8192
	s_waitcnt lgkmcnt(3)
	v_mfma_f32_32x32x16_bf16 v[96:111], v[6:9], v[124:127], v[96:111]
	v_add_u32_e32 v15, v0, v200
	ds_read_b128 v[2:5], v15
	s_waitcnt lgkmcnt(3)
	v_mfma_f32_32x32x16_bf16 v[80:95], v[10:13], v[124:127], v[80:95]
	ds_read_b128 v[6:9], v15 offset:8192
	s_waitcnt lgkmcnt(3)
	v_mfma_f32_32x32x16_bf16 v[96:111], v[246:249], v[128:131], v[96:111]
	v_add_u32_e32 v14, v0, v201
	ds_read_b128 v[10:13], v14
	s_waitcnt lgkmcnt(3)
	v_mfma_f32_32x32x16_bf16 v[80:95], v[250:253], v[128:131], v[80:95]
	ds_read_b128 v[246:249], v14 offset:8192
	s_waitcnt lgkmcnt(3)
	v_mfma_f32_32x32x16_bf16 v[96:111], v[2:5], v[132:135], v[96:111]
	v_add_u32_e32 v15, v0, v202
	ds_read_b128 v[250:253], v15
	s_waitcnt lgkmcnt(3)
	v_mfma_f32_32x32x16_bf16 v[80:95], v[6:9], v[132:135], v[80:95]
	ds_read_b128 v[2:5], v15 offset:8192
	s_waitcnt lgkmcnt(3)
	v_mfma_f32_32x32x16_bf16 v[96:111], v[10:13], v[136:139], v[96:111]
	s_waitcnt lgkmcnt(2)
	v_mfma_f32_32x32x16_bf16 v[80:95], v[246:249], v[136:139], v[80:95]
	s_waitcnt lgkmcnt(1)
	v_mfma_f32_32x32x16_bf16 v[96:111], v[250:253], v[140:143], v[96:111]
	s_waitcnt lgkmcnt(0)
	v_mfma_f32_32x32x16_bf16 v[80:95], v[2:5], v[140:143], v[80:95]
	s_cbranch_vccnz .LBB0_433
	v_add_u32_e32 v0, s57, v180
	v_add_u32_e32 v2, 32, v0
	v_cmp_le_i32_e32 vcc, v2, v172
	v_add_u32_e32 v2, 33, v0
	s_nop 6
	v_cndmask_b32_e32 v80, v195, v80, vcc
	v_cmp_lt_i32_e32 vcc, v0, v172
	s_nop 1
	v_cndmask_b32_e32 v97, v195, v97, vcc
	v_cmp_le_i32_e32 vcc, v0, v172
	s_nop 1
	v_cndmask_b32_e32 v96, v195, v96, vcc
	v_cmp_le_i32_e32 vcc, v2, v172
	v_add_u32_e32 v2, 2, v0
	s_nop 0
	v_cndmask_b32_e32 v81, v195, v81, vcc
	v_cmp_le_i32_e32 vcc, v2, v172
	v_add_u32_e32 v2, 34, v0
	s_nop 0
	v_cndmask_b32_e32 v98, v195, v98, vcc
	v_cmp_le_i32_e32 vcc, v2, v172
	v_add_u32_e32 v2, 3, v0
	s_nop 0
	v_cndmask_b32_e32 v82, v195, v82, vcc
	v_cmp_le_i32_e32 vcc, v2, v172
	v_add_u32_e32 v2, 35, v0
	s_nop 0
	v_cndmask_b32_e32 v99, v195, v99, vcc
	v_cmp_le_i32_e32 vcc, v2, v172
	v_add_u32_e32 v2, 8, v0
	s_nop 0
	v_cndmask_b32_e32 v83, v195, v83, vcc
	v_cmp_le_i32_e32 vcc, v2, v172
	v_add_u32_e32 v2, 40, v0
	s_nop 0
	v_cndmask_b32_e32 v100, v195, v100, vcc
	v_cmp_le_i32_e32 vcc, v2, v172
	v_add_u32_e32 v2, 9, v0
	s_nop 0
	v_cndmask_b32_e32 v84, v195, v84, vcc
	v_cmp_le_i32_e32 vcc, v2, v172
	v_add_u32_e32 v2, 41, v0
	s_nop 0
	v_cndmask_b32_e32 v101, v195, v101, vcc
	v_cmp_le_i32_e32 vcc, v2, v172
	v_add_u32_e32 v2, 10, v0
	s_nop 0
	v_cndmask_b32_e32 v85, v195, v85, vcc
	v_cmp_le_i32_e32 vcc, v2, v172
	v_add_u32_e32 v2, 42, v0
	s_nop 0
	v_cndmask_b32_e32 v102, v195, v102, vcc
	v_cmp_le_i32_e32 vcc, v2, v172
	v_add_u32_e32 v2, 11, v0
	s_nop 0
	v_cndmask_b32_e32 v86, v195, v86, vcc
	v_cmp_le_i32_e32 vcc, v2, v172
	v_add_u32_e32 v2, 43, v0
	s_nop 0
	v_cndmask_b32_e32 v103, v195, v103, vcc
	v_cmp_le_i32_e32 vcc, v2, v172
	v_add_u32_e32 v2, 16, v0
	s_nop 0
	v_cndmask_b32_e32 v87, v195, v87, vcc
	v_cmp_le_i32_e32 vcc, v2, v172
	v_add_u32_e32 v2, 48, v0
	s_nop 0
	v_cndmask_b32_e32 v104, v195, v104, vcc
	v_cmp_le_i32_e32 vcc, v2, v172
	v_add_u32_e32 v2, 17, v0
	s_nop 0
	v_cndmask_b32_e32 v88, v195, v88, vcc
	v_cmp_le_i32_e32 vcc, v2, v172
	v_add_u32_e32 v2, 49, v0
	s_nop 0
	v_cndmask_b32_e32 v105, v195, v105, vcc
	v_cmp_le_i32_e32 vcc, v2, v172
	v_add_u32_e32 v2, 18, v0
	s_nop 0
	v_cndmask_b32_e32 v89, v195, v89, vcc
	v_cmp_le_i32_e32 vcc, v2, v172
	v_add_u32_e32 v2, 50, v0
	s_nop 0
	v_cndmask_b32_e32 v106, v195, v106, vcc
	v_cmp_le_i32_e32 vcc, v2, v172
	v_add_u32_e32 v2, 19, v0
	s_nop 0
	v_cndmask_b32_e32 v90, v195, v90, vcc
	v_cmp_le_i32_e32 vcc, v2, v172
	v_add_u32_e32 v2, 51, v0
	s_nop 0
	v_cndmask_b32_e32 v107, v195, v107, vcc
	v_cmp_le_i32_e32 vcc, v2, v172
	v_add_u32_e32 v2, 24, v0
	s_nop 0
	v_cndmask_b32_e32 v91, v195, v91, vcc
	v_cmp_le_i32_e32 vcc, v2, v172
	v_add_u32_e32 v2, 56, v0
	s_nop 0
	v_cndmask_b32_e32 v108, v195, v108, vcc
	v_cmp_le_i32_e32 vcc, v2, v172
	v_add_u32_e32 v2, 25, v0
	s_nop 0
	v_cndmask_b32_e32 v92, v195, v92, vcc
	v_cmp_le_i32_e32 vcc, v2, v172
	v_add_u32_e32 v2, 57, v0
	s_nop 0
	v_cndmask_b32_e32 v109, v195, v109, vcc
	v_cmp_le_i32_e32 vcc, v2, v172
	v_add_u32_e32 v2, 26, v0
	s_nop 0
	v_cndmask_b32_e32 v93, v195, v93, vcc
	v_cmp_le_i32_e32 vcc, v2, v172
	v_add_u32_e32 v2, 58, v0
	s_nop 0
	v_cndmask_b32_e32 v110, v195, v110, vcc
	v_cmp_le_i32_e32 vcc, v2, v172
	v_add_u32_e32 v2, 27, v0
	v_add_u32_e32 v0, 59, v0
	v_cndmask_b32_e32 v94, v195, v94, vcc
	v_cmp_le_i32_e32 vcc, v2, v172
	s_nop 1
	v_cndmask_b32_e32 v111, v195, v111, vcc
	v_cmp_le_i32_e32 vcc, v0, v172
	s_nop 1
	v_cndmask_b32_e32 v95, v195, v95, vcc

.LBB0_435:
	v_sub_f32_e32 v8, v82, v2
	v_sub_f32_e32 v9, v83, v2
	v_sub_f32_e32 v7, v98, v2
	v_exp_f32_e32 v98, v8
	v_sub_f32_e32 v8, v99, v2
	v_exp_f32_e32 v99, v9
	v_sub_f32_e32 v9, v100, v2
	v_exp_f32_e32 v12, v9
	v_sub_f32_e32 v9, v84, v2
	v_exp_f32_e32 v100, v9
	v_sub_f32_e32 v9, v101, v2
	v_exp_f32_e32 v13, v9
	v_sub_f32_e32 v9, v85, v2
	v_exp_f32_e32 v101, v9
	v_sub_f32_e32 v9, v102, v2
	v_exp_f32_e32 v14, v9
	v_sub_f32_e32 v9, v86, v2
	v_exp_f32_e32 v102, v9
	v_sub_f32_e32 v9, v103, v2
	v_exp_f32_e32 v15, v9
	v_sub_f32_e32 v9, v87, v2
	v_sub_f32_e32 v3, v96, v2
	v_sub_f32_e32 v4, v80, v2
	v_exp_f32_e32 v103, v9
	v_sub_f32_e32 v9, v104, v2
	v_exp_f32_e32 v3, v3
	v_exp_f32_e32 v96, v4
	v_sub_f32_e32 v4, v97, v2
	v_sub_f32_e32 v5, v81, v2
	v_exp_f32_e32 v104, v9
	v_sub_f32_e32 v9, v88, v2
	v_exp_f32_e32 v4, v4
	v_exp_f32_e32 v97, v5
	v_exp_f32_e32 v88, v9
	v_sub_f32_e32 v9, v105, v2
	v_exp_f32_e32 v7, v7
	v_exp_f32_e32 v105, v9
	v_sub_f32_e32 v9, v89, v2
	v_exp_f32_e32 v8, v8
	v_exp_f32_e32 v89, v9
	v_sub_f32_e32 v9, v106, v2
	v_add_f32_e32 v5, v3, v96
	v_exp_f32_e32 v106, v9
	v_sub_f32_e32 v9, v90, v2
	v_add_f32_e32 v5, 0, v5
	v_add_f32_e32 v6, v4, v97
	v_exp_f32_e32 v90, v9
	v_sub_f32_e32 v9, v107, v2
	v_add_f32_e32 v5, v6, v5
	v_add_f32_e32 v6, v7, v98
	v_exp_f32_e32 v107, v9
	v_sub_f32_e32 v9, v91, v2
	v_add_f32_e32 v5, v6, v5
	v_add_f32_e32 v6, v8, v99
	v_exp_f32_e32 v91, v9
	v_sub_f32_e32 v9, v108, v2
	v_add_f32_e32 v5, v6, v5
	v_add_f32_e32 v6, v12, v100
	v_exp_f32_e32 v108, v9
	v_sub_f32_e32 v9, v92, v2
	v_add_f32_e32 v5, v6, v5
	v_add_f32_e32 v6, v13, v101
	v_exp_f32_e32 v92, v9
	v_sub_f32_e32 v9, v109, v2
	v_add_f32_e32 v5, v6, v5
	v_add_f32_e32 v6, v14, v102
	v_exp_f32_e32 v109, v9
	v_sub_f32_e32 v9, v93, v2
	v_add_f32_e32 v5, v6, v5
	v_add_f32_e32 v6, v15, v103
	v_exp_f32_e32 v93, v9
	v_sub_f32_e32 v9, v110, v2
	v_add_f32_e32 v5, v6, v5
	v_add_f32_e32 v6, v104, v88
	v_exp_f32_e32 v110, v9
	v_sub_f32_e32 v9, v94, v2
	v_add_f32_e32 v5, v6, v5
	v_add_f32_e32 v6, v105, v89
	v_exp_f32_e32 v94, v9
	v_sub_f32_e32 v9, v111, v2
	v_add_f32_e32 v5, v6, v5
	v_add_f32_e32 v6, v106, v90
	v_exp_f32_e32 v111, v9
	v_sub_f32_e32 v9, v95, v2
	v_add_f32_e32 v5, v6, v5
	v_add_f32_e32 v6, v107, v91
	v_exp_f32_e32 v95, v9
	v_add_f32_e32 v5, v6, v5
	v_add_f32_e32 v6, v108, v92
	v_add_f32_e32 v5, v6, v5
	v_add_f32_e32 v6, v109, v93
	v_add_f32_e32 v5, v6, v5
	v_add_f32_e32 v6, v110, v94
	v_add_f32_e32 v5, v6, v5
	v_add_f32_e32 v6, v111, v95
	v_add_f32_e32 v213, v6, v5
	v_fmac_f32_e32 v213, v212, v0
	s_add_i32 s0, s2, 0
	s_setprio 0
	v_add_u32_e32 v0, s0, v181
	v_add_u32_e32 v212, s0, v203
	v_cvt_pk_bf16_f32 v4, v3, v4
	v_add3_u32 v3, v0, v204, v203
	v_add3_u32 v86, v212, v205, v181
	v_cvt_pk_bf16_f32 v5, v7, v8
	ds_read_b64_tr_b16 v[8:9], v3 offset:32768
	ds_read_b64_tr_b16 v[10:11], v86 offset:34816
	v_cvt_pk_bf16_f32 v6, v12, v13
	v_cvt_pk_bf16_f32 v7, v14, v15
	ds_read_b64_tr_b16 v[12:13], v3 offset:36864
	ds_read_b64_tr_b16 v[80:81], v3 offset:40960
	ds_read_b64_tr_b16 v[84:85], v3 offset:45056
	ds_read_b64_tr_b16 v[14:15], v86 offset:38912
	ds_read_b64_tr_b16 v[82:83], v86 offset:43008
	ds_read_b64_tr_b16 v[86:87], v86 offset:47104
	s_waitcnt lgkmcnt(6)
	v_mfma_f32_32x32x16_bf16 v[64:79], v[8:11], v[4:7], v[64:79]
	v_cvt_pk_bf16_f32 v8, v104, v105
	v_cvt_pk_bf16_f32 v9, v106, v107
	v_cvt_pk_bf16_f32 v10, v108, v109
	v_cvt_pk_bf16_f32 v11, v110, v111
	v_add3_u32 v3, v0, v206, v203
	s_waitcnt lgkmcnt(2)
	v_mfma_f32_32x32x16_bf16 v[64:79], v[12:15], v[8:11], v[64:79]
	v_cvt_pk_bf16_f32 v12, v96, v97
	v_cvt_pk_bf16_f32 v13, v98, v99
	v_cvt_pk_bf16_f32 v14, v100, v101
	v_cvt_pk_bf16_f32 v15, v102, v103
	v_add3_u32 v100, v212, v207, v181
	s_waitcnt lgkmcnt(1)
	v_mfma_f32_32x32x16_bf16 v[64:79], v[80:83], v[12:15], v[64:79]
	v_cvt_pk_bf16_f32 v80, v88, v89
	ds_read_b64_tr_b16 v[88:89], v100 offset:34816
	v_cvt_pk_bf16_f32 v81, v90, v91
	v_cvt_pk_bf16_f32 v82, v92, v93
	v_cvt_pk_bf16_f32 v83, v94, v95
	s_waitcnt lgkmcnt(1)
	s_nop 0
	v_mfma_f32_32x32x16_bf16 v[64:79], v[84:87], v[80:83], v[64:79]
	ds_read_b64_tr_b16 v[86:87], v3 offset:32768
	ds_read_b64_tr_b16 v[90:91], v3 offset:36864
	ds_read_b64_tr_b16 v[94:95], v3 offset:40960
	ds_read_b64_tr_b16 v[98:99], v3 offset:45056
	ds_read_b64_tr_b16 v[92:93], v100 offset:38912
	ds_read_b64_tr_b16 v[96:97], v100 offset:43008
	ds_read_b64_tr_b16 v[100:101], v100 offset:47104
	v_add3_u32 v3, v0, v208, v203
	v_add3_u32 v0, v0, v210, v203
	s_waitcnt lgkmcnt(6)
	v_mfma_f32_32x32x16_bf16 v[48:63], v[86:89], v[4:7], v[48:63]
	s_waitcnt lgkmcnt(2)
	v_mfma_f32_32x32x16_bf16 v[48:63], v[90:93], v[8:11], v[48:63]
	s_waitcnt lgkmcnt(1)
	v_mfma_f32_32x32x16_bf16 v[48:63], v[94:97], v[12:15], v[48:63]
	s_waitcnt lgkmcnt(0)
	v_mfma_f32_32x32x16_bf16 v[48:63], v[98:101], v[80:83], v[48:63]
	v_add3_u32 v98, v212, v209, v181
	ds_read_b64_tr_b16 v[86:87], v98 offset:34816
	ds_read_b64_tr_b16 v[84:85], v3 offset:32768
	ds_read_b64_tr_b16 v[88:89], v3 offset:36864
	ds_read_b64_tr_b16 v[92:93], v3 offset:40960
	ds_read_b64_tr_b16 v[96:97], v3 offset:45056
	ds_read_b64_tr_b16 v[90:91], v98 offset:38912
	ds_read_b64_tr_b16 v[94:95], v98 offset:43008
	ds_read_b64_tr_b16 v[98:99], v98 offset:47104
	v_add3_u32 v3, v212, v211, v181
	v_mov_b32_e32 v212, v213
	s_waitcnt lgkmcnt(6)
	v_mfma_f32_32x32x16_bf16 v[32:47], v[84:87], v[4:7], v[32:47]
	s_waitcnt lgkmcnt(2)
	v_mfma_f32_32x32x16_bf16 v[32:47], v[88:91], v[8:11], v[32:47]
	s_waitcnt lgkmcnt(1)
	v_mfma_f32_32x32x16_bf16 v[32:47], v[92:95], v[12:15], v[32:47]
	s_waitcnt lgkmcnt(0)
	v_mfma_f32_32x32x16_bf16 v[32:47], v[96:99], v[80:83], v[32:47]
	ds_read_b64_tr_b16 v[86:87], v3 offset:34816
	ds_read_b64_tr_b16 v[84:85], v0 offset:32768
	ds_read_b64_tr_b16 v[88:89], v0 offset:36864
	ds_read_b64_tr_b16 v[92:93], v0 offset:40960
	ds_read_b64_tr_b16 v[96:97], v0 offset:45056
	ds_read_b64_tr_b16 v[90:91], v3 offset:38912
	ds_read_b64_tr_b16 v[94:95], v3 offset:43008
	ds_read_b64_tr_b16 v[98:99], v3 offset:47104
	s_waitcnt lgkmcnt(6)
	v_mfma_f32_32x32x16_bf16 v[16:31], v[84:87], v[4:7], v[16:31]
	s_waitcnt lgkmcnt(2)
	v_mfma_f32_32x32x16_bf16 v[16:31], v[88:91], v[8:11], v[16:31]
	s_waitcnt lgkmcnt(1)
	v_mfma_f32_32x32x16_bf16 v[16:31], v[92:95], v[12:15], v[16:31]
	s_waitcnt lgkmcnt(0)
	v_mfma_f32_32x32x16_bf16 v[16:31], v[96:99], v[80:83], v[16:31]
	s_add_i32 s57, s57, 64
	s_addk_i32 s55, 0x4000
	s_cmp_lg_u32 s56, s58
	s_cbranch_scc1 .LBB0_423

.LBB0_468:
	v_sub_f32_e32 v8, v82, v2
	v_sub_f32_e32 v9, v83, v2
	v_sub_f32_e32 v7, v98, v2
	v_exp_f32_e32 v98, v8
	v_sub_f32_e32 v8, v99, v2
	v_exp_f32_e32 v99, v9
	v_sub_f32_e32 v9, v100, v2
	v_exp_f32_e32 v12, v9
	v_sub_f32_e32 v9, v84, v2
	v_exp_f32_e32 v100, v9
	v_sub_f32_e32 v9, v101, v2
	v_exp_f32_e32 v13, v9
	v_sub_f32_e32 v9, v85, v2
	v_exp_f32_e32 v101, v9
	v_sub_f32_e32 v9, v102, v2
	v_exp_f32_e32 v14, v9
	v_sub_f32_e32 v9, v86, v2
	v_exp_f32_e32 v102, v9
	v_sub_f32_e32 v9, v103, v2
	v_exp_f32_e32 v15, v9
	v_sub_f32_e32 v9, v87, v2
	v_sub_f32_e32 v3, v96, v2
	v_sub_f32_e32 v4, v80, v2
	v_exp_f32_e32 v103, v9
	v_sub_f32_e32 v9, v104, v2
	v_exp_f32_e32 v3, v3
	v_exp_f32_e32 v96, v4
	v_sub_f32_e32 v4, v97, v2
	v_sub_f32_e32 v5, v81, v2
	v_exp_f32_e32 v104, v9
	v_sub_f32_e32 v9, v88, v2
	v_exp_f32_e32 v4, v4
	v_exp_f32_e32 v97, v5
	v_exp_f32_e32 v88, v9
	v_sub_f32_e32 v9, v105, v2
	v_exp_f32_e32 v7, v7
	v_exp_f32_e32 v105, v9
	v_sub_f32_e32 v9, v89, v2
	v_exp_f32_e32 v8, v8
	v_exp_f32_e32 v89, v9
	v_sub_f32_e32 v9, v106, v2
	v_add_f32_e32 v5, v3, v96
	v_exp_f32_e32 v106, v9
	v_sub_f32_e32 v9, v90, v2
	v_add_f32_e32 v5, 0, v5
	v_add_f32_e32 v6, v4, v97
	v_exp_f32_e32 v90, v9
	v_sub_f32_e32 v9, v107, v2
	v_add_f32_e32 v5, v6, v5
	v_add_f32_e32 v6, v7, v98
	v_exp_f32_e32 v107, v9
	v_sub_f32_e32 v9, v91, v2
	v_add_f32_e32 v5, v6, v5
	v_add_f32_e32 v6, v8, v99
	v_exp_f32_e32 v91, v9
	v_sub_f32_e32 v9, v108, v2
	v_add_f32_e32 v5, v6, v5
	v_add_f32_e32 v6, v12, v100
	v_exp_f32_e32 v108, v9
	v_sub_f32_e32 v9, v92, v2
	v_add_f32_e32 v5, v6, v5
	v_add_f32_e32 v6, v13, v101
	v_exp_f32_e32 v92, v9
	v_sub_f32_e32 v9, v109, v2
	v_add_f32_e32 v5, v6, v5
	v_add_f32_e32 v6, v14, v102
	v_exp_f32_e32 v109, v9
	v_sub_f32_e32 v9, v93, v2
	v_add_f32_e32 v5, v6, v5
	v_add_f32_e32 v6, v15, v103
	v_exp_f32_e32 v93, v9
	v_sub_f32_e32 v9, v110, v2
	v_add_f32_e32 v5, v6, v5
	v_add_f32_e32 v6, v104, v88
	v_exp_f32_e32 v110, v9
	v_sub_f32_e32 v9, v94, v2
	v_add_f32_e32 v5, v6, v5
	v_add_f32_e32 v6, v105, v89
	v_exp_f32_e32 v94, v9
	v_sub_f32_e32 v9, v111, v2
	v_add_f32_e32 v5, v6, v5
	v_add_f32_e32 v6, v106, v90
	v_exp_f32_e32 v111, v9
	v_sub_f32_e32 v9, v95, v2
	v_add_f32_e32 v5, v6, v5
	v_add_f32_e32 v6, v107, v91
	v_exp_f32_e32 v95, v9
	v_add_f32_e32 v5, v6, v5
	v_add_f32_e32 v6, v108, v92
	v_add_f32_e32 v5, v6, v5
	v_add_f32_e32 v6, v109, v93
	v_add_f32_e32 v5, v6, v5
	v_add_f32_e32 v6, v110, v94
	v_add_f32_e32 v5, v6, v5
	v_add_f32_e32 v6, v111, v95
	v_add_f32_e32 v213, v6, v5
	v_fmac_f32_e32 v213, v212, v0
	s_add_i32 s0, s2, 0
	s_setprio 0
	v_add_u32_e32 v0, s0, v181
	v_add_u32_e32 v212, s0, v203
	v_cvt_pk_bf16_f32 v4, v3, v4
	v_add3_u32 v3, v0, v204, v203
	v_add3_u32 v86, v212, v205, v181
	v_cvt_pk_bf16_f32 v5, v7, v8
	ds_read_b64_tr_b16 v[8:9], v3 offset:32768
	ds_read_b64_tr_b16 v[10:11], v86 offset:34816
	v_cvt_pk_bf16_f32 v6, v12, v13
	v_cvt_pk_bf16_f32 v7, v14, v15
	ds_read_b64_tr_b16 v[12:13], v3 offset:36864
	ds_read_b64_tr_b16 v[80:81], v3 offset:40960
	ds_read_b64_tr_b16 v[84:85], v3 offset:45056
	ds_read_b64_tr_b16 v[14:15], v86 offset:38912
	ds_read_b64_tr_b16 v[82:83], v86 offset:43008
	ds_read_b64_tr_b16 v[86:87], v86 offset:47104
	s_waitcnt lgkmcnt(6)
	v_mfma_f32_32x32x16_bf16 v[64:79], v[8:11], v[4:7], v[64:79]
	v_cvt_pk_bf16_f32 v8, v104, v105
	v_cvt_pk_bf16_f32 v9, v106, v107
	v_cvt_pk_bf16_f32 v10, v108, v109
	v_cvt_pk_bf16_f32 v11, v110, v111
	v_add3_u32 v3, v0, v206, v203
	s_waitcnt lgkmcnt(2)
	v_mfma_f32_32x32x16_bf16 v[64:79], v[12:15], v[8:11], v[64:79]
	v_cvt_pk_bf16_f32 v12, v96, v97
	v_cvt_pk_bf16_f32 v13, v98, v99
	v_cvt_pk_bf16_f32 v14, v100, v101
	v_cvt_pk_bf16_f32 v15, v102, v103
	v_add3_u32 v100, v212, v207, v181
	s_waitcnt lgkmcnt(1)
	v_mfma_f32_32x32x16_bf16 v[64:79], v[80:83], v[12:15], v[64:79]
	v_cvt_pk_bf16_f32 v80, v88, v89
	ds_read_b64_tr_b16 v[88:89], v100 offset:34816
	v_cvt_pk_bf16_f32 v81, v90, v91
	v_cvt_pk_bf16_f32 v82, v92, v93
	v_cvt_pk_bf16_f32 v83, v94, v95
	s_waitcnt lgkmcnt(1)
	s_nop 0
	v_mfma_f32_32x32x16_bf16 v[64:79], v[84:87], v[80:83], v[64:79]
	ds_read_b64_tr_b16 v[86:87], v3 offset:32768
	ds_read_b64_tr_b16 v[90:91], v3 offset:36864
	ds_read_b64_tr_b16 v[94:95], v3 offset:40960
	ds_read_b64_tr_b16 v[98:99], v3 offset:45056
	ds_read_b64_tr_b16 v[92:93], v100 offset:38912
	ds_read_b64_tr_b16 v[96:97], v100 offset:43008
	ds_read_b64_tr_b16 v[100:101], v100 offset:47104
	v_add3_u32 v3, v0, v208, v203
	v_add3_u32 v0, v0, v210, v203
	s_waitcnt lgkmcnt(6)
	v_mfma_f32_32x32x16_bf16 v[48:63], v[86:89], v[4:7], v[48:63]
	s_waitcnt lgkmcnt(2)
	v_mfma_f32_32x32x16_bf16 v[48:63], v[90:93], v[8:11], v[48:63]
	s_waitcnt lgkmcnt(1)
	v_mfma_f32_32x32x16_bf16 v[48:63], v[94:97], v[12:15], v[48:63]
	s_waitcnt lgkmcnt(0)
	v_mfma_f32_32x32x16_bf16 v[48:63], v[98:101], v[80:83], v[48:63]
	v_add3_u32 v98, v212, v209, v181
	ds_read_b64_tr_b16 v[86:87], v98 offset:34816
	ds_read_b64_tr_b16 v[84:85], v3 offset:32768
	ds_read_b64_tr_b16 v[88:89], v3 offset:36864
	ds_read_b64_tr_b16 v[92:93], v3 offset:40960
	ds_read_b64_tr_b16 v[96:97], v3 offset:45056
	ds_read_b64_tr_b16 v[90:91], v98 offset:38912
	ds_read_b64_tr_b16 v[94:95], v98 offset:43008
	ds_read_b64_tr_b16 v[98:99], v98 offset:47104
	v_add3_u32 v3, v212, v211, v181
	v_mov_b32_e32 v212, v213
	s_waitcnt lgkmcnt(6)
	v_mfma_f32_32x32x16_bf16 v[32:47], v[84:87], v[4:7], v[32:47]
	s_waitcnt lgkmcnt(2)
	v_mfma_f32_32x32x16_bf16 v[32:47], v[88:91], v[8:11], v[32:47]
	s_waitcnt lgkmcnt(1)
	v_mfma_f32_32x32x16_bf16 v[32:47], v[92:95], v[12:15], v[32:47]
	s_waitcnt lgkmcnt(0)
	v_mfma_f32_32x32x16_bf16 v[32:47], v[96:99], v[80:83], v[32:47]
	ds_read_b64_tr_b16 v[86:87], v3 offset:34816
	ds_read_b64_tr_b16 v[84:85], v0 offset:32768
	ds_read_b64_tr_b16 v[88:89], v0 offset:36864
	ds_read_b64_tr_b16 v[92:93], v0 offset:40960
	ds_read_b64_tr_b16 v[96:97], v0 offset:45056
	ds_read_b64_tr_b16 v[90:91], v3 offset:38912
	ds_read_b64_tr_b16 v[94:95], v3 offset:43008
	ds_read_b64_tr_b16 v[98:99], v3 offset:47104
	s_waitcnt lgkmcnt(6)
	v_mfma_f32_32x32x16_bf16 v[16:31], v[84:87], v[4:7], v[16:31]
	s_waitcnt lgkmcnt(2)
	v_mfma_f32_32x32x16_bf16 v[16:31], v[88:91], v[8:11], v[16:31]
	s_waitcnt lgkmcnt(1)
	v_mfma_f32_32x32x16_bf16 v[16:31], v[92:95], v[12:15], v[16:31]
	s_waitcnt lgkmcnt(0)
	v_mfma_f32_32x32x16_bf16 v[16:31], v[96:99], v[80:83], v[16:31]
	s_add_i32 s57, s57, 64
	s_addk_i32 s55, 0x4000
	s_cmp_lg_u32 s56, s58
	s_cbranch_scc1 .LBB0_456
	s_branch .LBB0_262

	.amdhsa_kernel _Z14fwd_megakernel4Args
		.amdhsa_group_segment_fixed_size 0
		.amdhsa_private_segment_fixed_size 0
		.amdhsa_kernarg_size 872
		.amdhsa_user_sgpr_count 2
		.amdhsa_user_sgpr_dispatch_ptr 0
		.amdhsa_user_sgpr_queue_ptr 0
		.amdhsa_user_sgpr_kernarg_segment_ptr 1
		.amdhsa_user_sgpr_dispatch_id 0
		.amdhsa_user_sgpr_kernarg_preload_length 0
		.amdhsa_user_sgpr_kernarg_preload_offset 0
		.amdhsa_user_sgpr_private_segment_size 0
		.amdhsa_uses_dynamic_stack 0
		.amdhsa_enable_private_segment 0
		.amdhsa_system_sgpr_workgroup_id_x 1
		.amdhsa_system_sgpr_workgroup_id_y 0
		.amdhsa_system_sgpr_workgroup_id_z 0
		.amdhsa_system_sgpr_workgroup_info 0
		.amdhsa_system_vgpr_workitem_id 2
		.amdhsa_next_free_vgpr 256
		.amdhsa_next_free_sgpr 98
		.amdhsa_accum_offset 256
		.amdhsa_reserve_vcc 1
		.amdhsa_float_round_mode_32 0
		.amdhsa_float_round_mode_16_64 0
		.amdhsa_float_denorm_mode_32 3
		.amdhsa_float_denorm_mode_16_64 3
		.amdhsa_dx10_clamp 1
		.amdhsa_ieee_mode 1
		.amdhsa_fp16_overflow 0
		.amdhsa_tg_split 0
		.amdhsa_exception_fp_ieee_invalid_op 0
		.amdhsa_exception_fp_denorm_src 0
		.amdhsa_exception_fp_ieee_div_zero 0
		.amdhsa_exception_fp_ieee_overflow 0
		.amdhsa_exception_fp_ieee_underflow 0
		.amdhsa_exception_fp_ieee_inexact 0
		.amdhsa_exception_int_div_zero 0
	.end_amdhsa_kernel

amdhsa.kernels:
  - .agpr_count:     0
    .args:
      - .offset:         0
        .size:           616
        .value_kind:     by_value
      - .offset:         616
        .size:           4
        .value_kind:     hidden_block_count_x
      - .offset:         620
        .size:           4
        .value_kind:     hidden_block_count_y
      - .offset:         624
        .size:           4
        .value_kind:     hidden_block_count_z
      - .offset:         628
        .size:           2
        .value_kind:     hidden_group_size_x
      - .offset:         630
        .size:           2
        .value_kind:     hidden_group_size_y
      - .offset:         632
        .size:           2
        .value_kind:     hidden_group_size_z
      - .offset:         634
        .size:           2
        .value_kind:     hidden_remainder_x
      - .offset:         636
        .size:           2
        .value_kind:     hidden_remainder_y
      - .offset:         638
        .size:           2
        .value_kind:     hidden_remainder_z
      - .offset:         656
        .size:           8
        .value_kind:     hidden_global_offset_x
      - .offset:         664
        .size:           8
        .value_kind:     hidden_global_offset_y
      - .offset:         672
        .size:           8
        .value_kind:     hidden_global_offset_z
      - .offset:         680
        .size:           2
        .value_kind:     hidden_grid_dims
      - .offset:         704
        .size:           8
        .value_kind:     hidden_multigrid_sync_arg
      - .offset:         736
        .size:           4
        .value_kind:     hidden_dynamic_lds_size
    .group_segment_fixed_size: 0
    .kernarg_segment_align: 8
    .kernarg_segment_size: 872
    .language:       OpenCL C
    .language_version:
      - 2
      - 0
    .max_flat_workgroup_size: 512
    .name:           _Z14fwd_megakernel4Args
    .private_segment_fixed_size: 0
    .sgpr_count:     104
    .sgpr_spill_count: 3
    .symbol:         _Z14fwd_megakernel4Args.kd
    .uniform_work_group_size: 1
    .uses_dynamic_stack: false
    .vgpr_count:     256
    .vgpr_spill_count: 0
    .wavefront_size: 64
